# P0 x->bf16 row loop: 4 rows (16 loads) issued per batch with counted waits, rows processed from copies; single-row fallback kept
# baseline (speedup 1.0000x reference)
; DI unsigned pk2(float a, float b) { f32x2 v = {a, b}; bf16x2_t r = __builtin_convertvector(v, bf16x2_t); return __builtin_bit_cast(unsigned, r); }
; DI void raw_row_to_bf16(const float* xrow, bf16_t* orow, float* rstd_out, int lane) {
;     const f32x4* xr = (const f32x4*)xrow + lane;
;     f32x4 v[4]; float s = 0.f;
; #pragma unroll
;     for (int j = 0; j < 4; ++j) { v[j] = __builtin_nontemporal_load(xr + 64 * j); s += (v[j].x * v[j].x + v[j].y * v[j].y) + (v[j].z * v[j].z + v[j].w * v[j].w); }
;     const float rstd = 1.0f / sqrtf(wave_sum(s, lane) * (1.f / DM) + EPS);
;     unsigned long long* o8 = (unsigned long long*)orow + lane;
; #pragma unroll
;     for (int j = 0; j < 4; ++j) o8[64 * j] = (unsigned long long)pk2(v[j].x, v[j].y) | ((unsigned long long)pk2(v[j].z, v[j].w) << 32);
;     if (lane == 0) *rstd_out = rstd;
; }
; __global__ void __launch_bounds__(NTHR, 2) hybrid_fwd(Args a_unused) {
;     ...
;     { PH_BEGIN;
; #pragma unroll 1
;       for (int m = gw; m < M; m += ngw) raw_row_to_bf16(ap->in[0] + (size_t)m * DM, (bf16_t*)H + (size_t)m * DM, (float*)(ws + WS_RSTD) + m, lane); }
.LBB0_218:
	s_or_b64 exec, exec, s[14:15]
	s_add_i32 s2, s2, s70
	s_add_u32 s6, s6, s8
	s_addc_u32 s7, s7, s9
	v_lshl_add_u64 v[0:1], v[0:1], 0, s[10:11]
	v_lshl_add_u64 v[2:3], v[2:3], 0, s[12:13]
	s_cmp_eq_u32 s16, 1
	s_cbranch_scc1 .Lmy_x_b1
	s_cmp_eq_u32 s16, 2
	s_cbranch_scc1 .Lmy_x_b2
	s_cmp_eq_u32 s16, 3
	s_cbranch_scc1 .Lmy_x_b3
	s_cmpk_gt_i32 s2, 0x7fff
	s_cbranch_scc1 .LBB0_221
.LBB0_219:
	s_waitcnt lgkmcnt(0)
	s_mul_i32 s17, s70, 3
	s_add_i32 s17, s17, s2
	s_cmpk_gt_i32 s17, 0x7fff
	s_cbranch_scc1 .Lmy_x_single
	global_load_dwordx4 v[40:43], v[0:1], off offset:-3072 nt
	global_load_dwordx4 v[44:47], v[0:1], off offset:-2048 nt
	global_load_dwordx4 v[48:51], v[0:1], off offset:-1024 nt
	global_load_dwordx4 v[52:55], v[0:1], off nt
	v_lshl_add_u64 v[56:57], v[0:1], 0, s[10:11]
	global_load_dwordx4 v[60:63], v[56:57], off offset:-3072 nt
	global_load_dwordx4 v[64:67], v[56:57], off offset:-2048 nt
	global_load_dwordx4 v[68:71], v[56:57], off offset:-1024 nt
	global_load_dwordx4 v[72:75], v[56:57], off nt
	v_lshl_add_u64 v[56:57], v[56:57], 0, s[10:11]
	global_load_dwordx4 v[76:79], v[56:57], off offset:-3072 nt
	global_load_dwordx4 v[80:83], v[56:57], off offset:-2048 nt
	global_load_dwordx4 v[84:87], v[56:57], off offset:-1024 nt
	global_load_dwordx4 v[88:91], v[56:57], off nt
	v_lshl_add_u64 v[56:57], v[56:57], 0, s[10:11]
	global_load_dwordx4 v[100:103], v[56:57], off offset:-3072 nt
	global_load_dwordx4 v[104:107], v[56:57], off offset:-2048 nt
	global_load_dwordx4 v[108:111], v[56:57], off offset:-1024 nt
	global_load_dwordx4 v[112:115], v[56:57], off nt
	s_waitcnt vmcnt(12)
	v_mov_b32_e32 v14, v40
	v_mov_b32_e32 v15, v41
	v_mov_b32_e32 v16, v42
	v_mov_b32_e32 v17, v43
	v_mov_b32_e32 v18, v44
	v_mov_b32_e32 v19, v45
	v_mov_b32_e32 v20, v46
	v_mov_b32_e32 v21, v47
	v_mov_b32_e32 v22, v48
	v_mov_b32_e32 v23, v49
	v_mov_b32_e32 v24, v50
	v_mov_b32_e32 v25, v51
	v_mov_b32_e32 v26, v52
	v_mov_b32_e32 v27, v53
	v_mov_b32_e32 v28, v54
	v_mov_b32_e32 v29, v55
	s_mov_b32 s16, 1
	s_branch .Lmy_x_proc
.Lmy_x_b1:
	s_waitcnt vmcnt(12)
	v_mov_b32_e32 v14, v60
	v_mov_b32_e32 v15, v61
	v_mov_b32_e32 v16, v62
	v_mov_b32_e32 v17, v63
	v_mov_b32_e32 v18, v64
	v_mov_b32_e32 v19, v65
	v_mov_b32_e32 v20, v66
	v_mov_b32_e32 v21, v67
	v_mov_b32_e32 v22, v68
	v_mov_b32_e32 v23, v69
	v_mov_b32_e32 v24, v70
	v_mov_b32_e32 v25, v71
	v_mov_b32_e32 v26, v72
	v_mov_b32_e32 v27, v73
	v_mov_b32_e32 v28, v74
	v_mov_b32_e32 v29, v75
	s_mov_b32 s16, 2
	s_branch .Lmy_x_proc
.Lmy_x_b2:
	s_waitcnt vmcnt(12)
	v_mov_b32_e32 v14, v76
	v_mov_b32_e32 v15, v77
	v_mov_b32_e32 v16, v78
	v_mov_b32_e32 v17, v79
	v_mov_b32_e32 v18, v80
	v_mov_b32_e32 v19, v81
	v_mov_b32_e32 v20, v82
	v_mov_b32_e32 v21, v83
	v_mov_b32_e32 v22, v84
	v_mov_b32_e32 v23, v85
	v_mov_b32_e32 v24, v86
	v_mov_b32_e32 v25, v87
	v_mov_b32_e32 v26, v88
	v_mov_b32_e32 v27, v89
	v_mov_b32_e32 v28, v90
	v_mov_b32_e32 v29, v91
	s_mov_b32 s16, 3
	s_branch .Lmy_x_proc
.Lmy_x_b3:
	s_waitcnt vmcnt(12)
	v_mov_b32_e32 v14, v100
	v_mov_b32_e32 v15, v101
	v_mov_b32_e32 v16, v102
	v_mov_b32_e32 v17, v103
	v_mov_b32_e32 v18, v104
	v_mov_b32_e32 v19, v105
	v_mov_b32_e32 v20, v106
	v_mov_b32_e32 v21, v107
	v_mov_b32_e32 v22, v108
	v_mov_b32_e32 v23, v109
	v_mov_b32_e32 v24, v110
	v_mov_b32_e32 v25, v111
	v_mov_b32_e32 v26, v112
	v_mov_b32_e32 v27, v113
	v_mov_b32_e32 v28, v114
	v_mov_b32_e32 v29, v115
	s_mov_b32 s16, 0
	s_branch .Lmy_x_proc
.Lmy_x_single:
	global_load_dwordx4 v[14:17], v[0:1], off offset:-3072 nt
	global_load_dwordx4 v[18:21], v[0:1], off offset:-2048 nt
	global_load_dwordx4 v[22:25], v[0:1], off offset:-1024 nt
	global_load_dwordx4 v[26:29], v[0:1], off nt
	s_waitcnt vmcnt(0)
	s_mov_b32 s16, 0
.Lmy_x_proc:
	v_mul_f32_e32 v13, v15, v15
	v_mul_f32_e32 v30, v17, v17
	v_mul_f32_e32 v31, v19, v19
	v_mul_f32_e32 v32, v21, v21
	v_mul_f32_e32 v33, v23, v23
	v_mul_f32_e32 v34, v25, v25
	v_fmac_f32_e32 v13, v14, v14
	v_fmac_f32_e32 v30, v16, v16
	v_fmac_f32_e32 v31, v18, v18
	v_fmac_f32_e32 v32, v20, v20
	v_mul_f32_e32 v35, v27, v27
	v_mul_f32_e32 v36, v29, v29
	v_fmac_f32_e32 v33, v22, v22
	v_fmac_f32_e32 v34, v24, v24
	v_add_f32_e32 v13, v13, v30
	v_add_f32_e32 v30, v31, v32
	v_fmac_f32_e32 v35, v26, v26
	v_fmac_f32_e32 v36, v28, v28
	v_add_f32_e32 v31, v33, v34
	v_add_f32_e32 v13, v13, v30
	v_add_f32_e32 v32, v35, v36
	v_add_f32_e32 v13, v13, v31
	v_add_f32_e32 v13, v13, v32
	ds_bpermute_b32 v30, v4, v13
	v_cvt_pk_bf16_f32 v14, v14, v15
	v_cvt_pk_bf16_f32 v15, v16, v17
	v_cvt_pk_bf16_f32 v16, v18, v19
	v_cvt_pk_bf16_f32 v17, v20, v21
	s_waitcnt lgkmcnt(0)
	v_add_f32_e32 v13, v13, v30
	ds_bpermute_b32 v30, v5, v13
	global_store_dwordx2 v[2:3], v[14:15], off offset:-1024
	global_store_dwordx2 v[2:3], v[16:17], off offset:-512
	v_cvt_pk_bf16_f32 v18, v22, v23
	v_cvt_pk_bf16_f32 v16, v26, v27
	v_cvt_pk_bf16_f32 v17, v28, v29
	s_waitcnt lgkmcnt(0)
	v_add_f32_e32 v13, v13, v30
	ds_bpermute_b32 v30, v6, v13
	global_store_dwordx2 v[2:3], v[16:17], off offset:512
	s_waitcnt lgkmcnt(0)
	v_add_f32_e32 v13, v13, v30
	ds_bpermute_b32 v30, v7, v13
	s_waitcnt lgkmcnt(0)
	v_add_f32_e32 v13, v13, v30
	ds_bpermute_b32 v19, v8, v13
	s_waitcnt lgkmcnt(0)
	v_add_f32_e32 v13, v13, v19
	ds_bpermute_b32 v14, v9, v13
	v_cvt_pk_bf16_f32 v19, v24, v25
	global_store_dwordx2 v[2:3], v[18:19], off
	s_and_saveexec_b64 s[14:15], s[0:1]
	s_cbranch_execz .LBB0_218
	s_waitcnt lgkmcnt(0)
	v_add_f32_e32 v13, v13, v14
	v_fmamk_f32 v13, v13, 0x3a800000, v10
	v_mul_f32_e32 v14, 0x4f800000, v13
	v_cmp_gt_f32_e32 vcc, s3, v13
	s_nop 1
	v_cndmask_b32_e32 v13, v13, v14, vcc
	v_sqrt_f32_e32 v14, v13
	s_nop 0
	v_add_u32_e32 v15, -1, v14
	v_fma_f32 v17, -v15, v14, v13
	v_add_u32_e32 v16, 1, v14
	v_cmp_ge_f32_e64 s[4:5], 0, v17
	s_nop 1
	v_cndmask_b32_e64 v15, v14, v15, s[4:5]
	v_fma_f32 v14, -v16, v14, v13
	v_cmp_lt_f32_e64 s[4:5], 0, v14
	s_nop 1
	v_cndmask_b32_e64 v14, v15, v16, s[4:5]
	v_mul_f32_e32 v15, 0x37800000, v14
	v_cndmask_b32_e32 v14, v14, v15, vcc
	v_cmp_class_f32_e32 vcc, v13, v11
	s_nop 1
	v_cndmask_b32_e32 v13, v14, v13, vcc
	v_div_scale_f32 v14, s[4:5], v13, v13, 1.0
	v_rcp_f32_e32 v15, v14
	s_nop 0
	v_fma_f32 v16, -v14, v15, 1.0
	v_fmac_f32_e32 v15, v16, v15
	v_div_scale_f32 v16, vcc, 1.0, v13, 1.0
	v_mul_f32_e32 v17, v16, v15
	v_fma_f32 v18, -v14, v17, v16
	v_fmac_f32_e32 v17, v18, v15
	v_fma_f32 v14, -v14, v17, v16
	v_div_fmas_f32 v14, v14, v15, v17
	v_div_fixup_f32 v13, v14, v13, 1.0
	global_store_dword v12, v13, s[6:7]
	s_branch .LBB0_218
